# d4 + SwiGLU epilogue row-stat shuffles via v_permlane16/32_swap instead of ds_bpermute (phases 1 and 8)
# speedup vs baseline: 1.0153x; 1.0016x over previous
; #define LAS __attribute__((address_space(3)))
; __device__ __forceinline__ f32x4 sig_from_negl2(f32x4 t) { return rcp_4(exp2_4(t) + 1.0f); }
; __device__ __forceinline__ u32x2 pack4(f32x4 v) { u32x2 w; w.x = cvtpk(v[0], v[1]); w.y = cvtpk(v[2], v[3]); return w; }
; __device__ __forceinline__ void rstd8_lds(int rrel, int fq, float inv_dim, float (&rs)[2][4]) {
;     const LAS unsigned char* lds = (const LAS unsigned char*)0;
;     f32x4 v[2][4];
; #pragma unroll
;     for (int ai = 0; ai < 2; ++ai)
; #pragma unroll
;         for (int m = 0; m < 4; ++m) v[ai][m] = *(const LAS f32x4*)(lds + STAB_OFF + (rrel + ai * 128 + m * 16) * 64 + fq * 16);
; #pragma unroll
;     for (int ai = 0; ai < 2; ++ai)
; #pragma unroll
;         for (int m = 0; m < 4; ++m) { float q = (v[ai][m][0] + v[ai][m][1]) + (v[ai][m][2] + v[ai][m][3]); q += __shfl_xor(q, 16); q += __shfl_xor(q, 32); rs[ai][m] = __builtin_amdgcn_rsqf(q * inv_dim + EPS); }
; }
;     __device__ __forceinline__ void operator()(const Acc& acc, const Unit& u, int wr, int wc, int fr, int fq) const {
;         const int col = u.pn * 128 + wc * 32 + fq * 8;
;         float rsv[2][4]; rstd8_lds(wr * 64 + fr, fq, 1.0f / 1024.0f, rsv);
; #pragma unroll
;         for (int ai = 0; ai < 2; ++ai)
; #pragma unroll
;             for (int m = 0; m < 4; ++m) {
;                 const int r = u.pm * 256 + ai * 128 + wr * 64 + m * 16 + fr;
;                 const float rs = rsv[ai][m], nrs = -LOG2E * rs, rs2 = rs * rs;
;                 u32x4 w;
; #pragma unroll
;                 for (int n = 0; n < 2; ++n) {
;                     const f32x4 ga = acc[ai][0][m][n], ua = acc[ai][1][m][n];
;                     const f32x4 sg = sig_from_negl2(ga * nrs);
;                     const u32x2 pk = pack4((ga * ua) * rs2 * sg);
;                     if (n == 0) { w.x = pk.x; w.y = pk.y; } else { w.z = pk.x; w.w = pk.y; }
;                 }
;                 *(u32x4*)(O + (size_t)r * DFF + col) = w;
;             }
.LBB0_137:
	ds_read_b128 v[156:159], v153
	ds_read_b128 v[160:163], v153 offset:1024
	ds_read_b128 v[164:167], v153 offset:2048
	ds_read_b128 v[172:175], v153 offset:3072
	v_and_b32_e32 v176, 64, v154
	v_xor_b32_e32 v169, 16, v154
	v_add_u32_e32 v178, 64, v176
	v_cmp_lt_i32_e32 vcc, v169, v178
	s_waitcnt lgkmcnt(0)
	v_mov_b32_e32 v176, v157
	v_mov_b32_e32 v177, v158
	v_mov_b32_e32 v157, v159
	v_cndmask_b32_e32 v169, v154, v169, vcc
	v_pk_add_f32 v[156:157], v[176:177], v[156:157]
	v_lshlrev_b32_e32 v169, 2, v169
	v_add_f32_e32 v156, v156, v157
	v_xor_b32_e32 v158, 32, v154
	v_cmp_lt_i32_e32 vcc, v158, v178
	v_pk_mul_f32 v[124:125], v[128:129], v[124:125]
	v_pk_mul_f32 v[122:123], v[126:127], v[122:123]
	v_cndmask_b32_e32 v158, v154, v158, vcc
	v_lshlrev_b32_e32 v190, 2, v158
	s_waitcnt lgkmcnt(0)
	v_mov_b32_e32 v247, v156
	v_mov_b32_e32 v157, v156
	s_nop 1
	v_permlane16_swap_b32_e32 v157, v247
	v_add_f32_e32 v188, v157, v247
	ds_read_b128 v[156:159], v153 offset:8192
	ds_read_b128 v[176:179], v153 offset:9216
	ds_read_b128 v[180:183], v153 offset:10240
	ds_read_b128 v[184:187], v153 offset:11264
	v_pk_mul_f32 v[114:115], v[118:119], v[114:115]
	v_pk_mul_f32 v[116:117], v[120:121], v[116:117]
	v_lshl_or_b32 v168, s62, 7, v149
	s_waitcnt lgkmcnt(0)
	v_mov_b32_e32 v247, v188
	v_mov_b32_e32 v189, v188
	s_nop 1
	v_permlane32_swap_b32_e32 v189, v247
	v_add_f32_e32 v191, v189, v247
	v_mov_b32_e32 v188, v161
	v_mov_b32_e32 v189, v162
	v_mov_b32_e32 v161, v163
	v_pk_add_f32 v[160:161], v[188:189], v[160:161]
	v_pk_mul_f32 v[106:107], v[110:111], v[106:107]
	v_add_f32_e32 v162, v160, v161
	v_mov_b32_e32 v160, v165
	v_mov_b32_e32 v161, v166
	v_mov_b32_e32 v165, v167
	v_pk_add_f32 v[160:161], v[160:161], v[164:165]
	v_add_f32_e32 v160, v160, v161
	v_fmamk_f32 v164, v191, 0x3a800000, v155
	v_rsq_f32_e32 v166, v164
	s_waitcnt lgkmcnt(0)
	v_mov_b32_e32 v247, v162
	v_mov_b32_e32 v163, v162
	s_nop 1
	v_permlane16_swap_b32_e32 v163, v247
	v_add_f32_e32 v162, v163, v247
	v_mov_b32_e32 v247, v160
	v_mov_b32_e32 v161, v160
	s_nop 1
	v_permlane16_swap_b32_e32 v161, v247
	v_add_f32_e32 v164, v161, v247
	v_mov_b32_e32 v160, v173
	v_mov_b32_e32 v161, v174
	v_mov_b32_e32 v173, v175
	v_pk_add_f32 v[160:161], v[160:161], v[172:173]
	s_waitcnt lgkmcnt(0)
	v_mov_b32_e32 v247, v162
	v_mov_b32_e32 v163, v162
	s_nop 1
	v_permlane32_swap_b32_e32 v163, v247
	v_add_f32_e32 v162, v163, v247
	v_add_f32_e32 v160, v160, v161
	v_fmamk_f32 v162, v162, 0x3a800000, v155
	v_rsq_f32_e32 v167, v162
	v_pk_mul_f32 v[108:109], v[112:113], v[108:109]
	s_waitcnt lgkmcnt(0)
	v_mov_b32_e32 v247, v160
	v_mov_b32_e32 v161, v160
	s_nop 1
	v_permlane16_swap_b32_e32 v161, v247
	v_add_f32_e32 v163, v161, v247
	v_mov_b32_e32 v160, v157
	v_mov_b32_e32 v161, v158
	v_mov_b32_e32 v157, v159
	v_pk_add_f32 v[156:157], v[160:161], v[156:157]
	v_mov_b32_e32 v247, v164
	v_mov_b32_e32 v165, v164
	s_nop 1
	v_permlane32_swap_b32_e32 v165, v247
	v_add_f32_e32 v162, v165, v247
	v_add_f32_e32 v156, v156, v157
	v_fmamk_f32 v158, v162, 0x3a800000, v155
	v_rsq_f32_e32 v159, v158
	v_pk_mul_f32 v[100:101], v[104:105], v[100:101]
	s_waitcnt lgkmcnt(0)
	v_mov_b32_e32 v247, v156
	v_mov_b32_e32 v157, v156
	s_nop 1
	v_permlane16_swap_b32_e32 v157, v247
	v_add_f32_e32 v160, v157, v247
	v_mov_b32_e32 v156, v177
	v_mov_b32_e32 v157, v178
	v_mov_b32_e32 v177, v179
	v_pk_add_f32 v[156:157], v[156:157], v[176:177]
	v_mov_b32_e32 v247, v163
	v_mov_b32_e32 v164, v163
	s_nop 1
	v_permlane32_swap_b32_e32 v164, v247
	v_add_f32_e32 v158, v164, v247
	v_add_f32_e32 v156, v156, v157
	v_fmamk_f32 v158, v158, 0x3a800000, v155
	v_rsq_f32_e32 v172, v158
	s_waitcnt lgkmcnt(0)
	v_mov_b32_e32 v247, v160
	v_mov_b32_e32 v161, v160
	s_nop 1
	v_permlane32_swap_b32_e32 v161, v247
	v_add_f32_e32 v158, v161, v247
	v_fmamk_f32 v158, v158, 0x3a800000, v155
	v_rsq_f32_e32 v161, v158
	v_mov_b32_e32 v247, v156
	v_mov_b32_e32 v157, v156
	s_nop 1
	v_permlane16_swap_b32_e32 v157, v247
	v_add_f32_e32 v158, v157, v247
	v_mov_b32_e32 v156, v181
	v_mov_b32_e32 v157, v182
	v_mov_b32_e32 v181, v183
	v_pk_add_f32 v[156:157], v[156:157], v[180:181]
	v_add_f32_e32 v162, v156, v157
	v_mov_b32_e32 v156, v185
	v_mov_b32_e32 v157, v186
	s_waitcnt lgkmcnt(0)
	v_mov_b32_e32 v247, v158
	v_mov_b32_e32 v160, v158
	s_nop 1
	v_permlane32_swap_b32_e32 v160, v247
	v_add_f32_e32 v158, v160, v247
	v_fmamk_f32 v158, v158, 0x3a800000, v155
	v_mov_b32_e32 v247, v162
	v_mov_b32_e32 v163, v162
	s_nop 1
	v_permlane16_swap_b32_e32 v163, v247
	v_add_f32_e32 v160, v163, v247
	v_rsq_f32_e32 v173, v158
	v_mov_b32_e32 v185, v187
	v_pk_add_f32 v[156:157], v[156:157], v[184:185]
	v_pk_mul_f32 v[98:99], v[102:103], v[98:99]
	s_waitcnt lgkmcnt(0)
	v_mov_b32_e32 v247, v160
	v_mov_b32_e32 v162, v160
	s_nop 1
	v_permlane32_swap_b32_e32 v162, v247
	v_add_f32_e32 v158, v162, v247
	v_mul_f32_e32 v160, 0xbfb8aa3b, v166
	v_pk_mul_f32 v[162:163], v[128:129], v[160:161] op_sel_hi:[1,0]
	v_pk_mul_f32 v[164:165], v[126:127], v[160:161] op_sel_hi:[1,0]
	v_exp_f32_e32 v162, v162
	v_exp_f32_e32 v164, v164
	v_exp_f32_e32 v163, v163
	v_exp_f32_e32 v165, v165
	v_add_f32_e32 v156, v156, v157
	v_pk_add_f32 v[162:163], v[162:163], 1.0 op_sel_hi:[1,0]
	v_pk_add_f32 v[164:165], v[164:165], 1.0 op_sel_hi:[1,0]
	v_rcp_f32_e32 v162, v162
	v_rcp_f32_e32 v164, v164
	v_rcp_f32_e32 v165, v165
	v_rcp_f32_e32 v163, v163
	v_pk_mul_f32 v[126:127], v[120:121], v[160:161] op_sel_hi:[1,0]
	v_pk_mul_f32 v[128:129], v[118:119], v[160:161] op_sel_hi:[1,0]
	v_exp_f32_e32 v126, v126
	v_exp_f32_e32 v128, v128
	v_exp_f32_e32 v127, v127
	v_exp_f32_e32 v129, v129
	v_mul_f32_e32 v166, v166, v166
	v_pk_mul_f32 v[122:123], v[122:123], v[166:167] op_sel_hi:[1,0]
	v_pk_mul_f32 v[124:125], v[124:125], v[166:167] op_sel_hi:[1,0]
	s_waitcnt lgkmcnt(0)
; __device__ __forceinline__ f32x4 sig_from_negl2(f32x4 t) { return rcp_4(exp2_4(t) + 1.0f); }
; __device__ __forceinline__ u32x2 pack4(f32x4 v) { u32x2 w; w.x = cvtpk(v[0], v[1]); w.y = cvtpk(v[2], v[3]); return w; }
; __device__ __forceinline__ void rstd8_lds(int rrel, int fq, float inv_dim, float (&rs)[2][4]) {
;     ...
;         for (int m = 0; m < 4; ++m) { float q = (v[ai][m][0] + v[ai][m][1]) + (v[ai][m][2] + v[ai][m][3]); q += __shfl_xor(q, 16); q += __shfl_xor(q, 32); rs[ai][m] = __builtin_amdgcn_rsqf(q * inv_dim + EPS); }
;     __device__ __forceinline__ void operator()(const Acc& acc, const Unit& u, int wr, int wc, int fr, int fq) const {
;     ...
;             for (int m = 0; m < 4; ++m) {
;                 const int r = u.pm * 256 + ai * 128 + wr * 64 + m * 16 + fr;
;                 const float rs = rsv[ai][m], nrs = -LOG2E * rs, rs2 = rs * rs;
;                 u32x4 w;
; #pragma unroll
;                 for (int n = 0; n < 2; ++n) {
;                     const f32x4 ga = acc[ai][0][m][n], ua = acc[ai][1][m][n];
;                     const f32x4 sg = sig_from_negl2(ga * nrs);
;                     const u32x2 pk = pack4((ga * ua) * rs2 * sg);
;                     if (n == 0) { w.x = pk.x; w.y = pk.y; } else { w.z = pk.x; w.w = pk.y; }
;                 }
;                 *(u32x4*)(O + (size_t)r * DFF + col) = w;
;             }
	v_mov_b32_e32 v247, v156
	v_mov_b32_e32 v157, v156
	s_nop 1
	v_permlane16_swap_b32_e32 v157, v247
	v_add_f32_e32 v156, v157, v247
	v_pk_mul_f32 v[124:125], v[124:125], v[162:163]
	v_pk_mul_f32 v[122:123], v[122:123], v[164:165]
	v_cvt_pk_bf16_f32 v122, v122, v123
	v_cvt_pk_bf16_f32 v123, v124, v125
	v_pk_add_f32 v[124:125], v[126:127], 1.0 op_sel_hi:[1,0]
	v_pk_add_f32 v[126:127], v[128:129], 1.0 op_sel_hi:[1,0]
	v_rcp_f32_e32 v124, v124
	v_rcp_f32_e32 v126, v126
	v_rcp_f32_e32 v127, v127
	v_rcp_f32_e32 v125, v125
	v_pk_mul_f32 v[114:115], v[114:115], v[166:167] op_sel_hi:[1,0]
	v_mul_f32_e32 v120, 0xbfb8aa3b, v167
	s_waitcnt lgkmcnt(0)
	v_mov_b32_e32 v247, v156
	v_mov_b32_e32 v157, v156
	s_nop 1
	v_permlane32_swap_b32_e32 v157, v247
	v_add_f32_e32 v156, v157, v247
	v_pk_mul_f32 v[114:115], v[114:115], v[126:127]
	v_pk_mul_f32 v[126:127], v[112:113], v[120:121] op_sel_hi:[1,0]
	v_pk_mul_f32 v[128:129], v[110:111], v[120:121] op_sel_hi:[1,0]
	v_fmamk_f32 v156, v156, 0x3a800000, v155
	v_pk_mul_f32 v[116:117], v[116:117], v[166:167] op_sel_hi:[1,0]
	v_exp_f32_e32 v128, v128
	v_exp_f32_e32 v126, v126
	v_exp_f32_e32 v127, v127
	v_exp_f32_e32 v129, v129
	v_rsq_f32_e32 v157, v156
	v_lshl_add_u32 v156, s60, 8, v1
	v_ashrrev_i32_e32 v169, 31, v168
	v_pk_mul_f32 v[116:117], v[116:117], v[124:125]
	v_cvt_pk_bf16_f32 v124, v114, v115
	v_mov_b64_e32 v[114:115], s[16:17]
	v_cvt_pk_bf16_f32 v125, v116, v117
	v_mad_i64_i32 v[118:119], s[64:65], v156, s85, v[114:115]
	v_lshlrev_b64 v[116:117], 1, v[168:169]
	v_lshl_add_u64 v[118:119], v[118:119], 0, v[116:117]
	global_store_dwordx4 v[118:119], v[122:125], off
	v_pk_mul_f32 v[110:111], v[104:105], v[120:121] op_sel_hi:[1,0]
	v_mul_f32_e32 v118, v167, v167
	v_pk_add_f32 v[122:123], v[126:127], 1.0 op_sel_hi:[1,0]
	v_pk_add_f32 v[124:125], v[128:129], 1.0 op_sel_hi:[1,0]
	v_rcp_f32_e32 v122, v122
	v_rcp_f32_e32 v124, v124
	v_rcp_f32_e32 v125, v125
	v_rcp_f32_e32 v123, v123
	v_exp_f32_e32 v110, v110
	v_exp_f32_e32 v111, v111
	v_pk_mul_f32 v[106:107], v[106:107], v[118:119] op_sel_hi:[1,0]
	v_pk_mul_f32 v[108:109], v[108:109], v[118:119] op_sel_hi:[1,0]
	v_pk_mul_f32 v[106:107], v[106:107], v[124:125]
	v_pk_mul_f32 v[108:109], v[108:109], v[122:123]
	v_cvt_pk_bf16_f32 v106, v106, v107
	v_cvt_pk_bf16_f32 v107, v108, v109
	v_pk_add_f32 v[108:109], v[110:111], 1.0 op_sel_hi:[1,0]
	v_pk_mul_f32 v[112:113], v[102:103], v[120:121] op_sel_hi:[1,0]
	v_rcp_f32_e32 v108, v108
	v_rcp_f32_e32 v109, v109
	v_exp_f32_e32 v112, v112
	v_exp_f32_e32 v113, v113
	v_pk_mul_f32 v[100:101], v[100:101], v[118:119] op_sel_hi:[1,0]
	v_pk_mul_f32 v[98:99], v[98:99], v[118:119] op_sel_hi:[1,0]
	v_pk_mul_f32 v[100:101], v[100:101], v[108:109]
	v_pk_add_f32 v[110:111], v[112:113], 1.0 op_sel_hi:[1,0]
	v_cvt_pk_bf16_f32 v109, v100, v101
	v_mul_f32_e32 v100, 0xbfb8aa3b, v159
	v_rcp_f32_e32 v110, v110
	v_rcp_f32_e32 v111, v111
	v_pk_mul_f32 v[102:103], v[96:97], v[100:101] op_sel_hi:[1,0]
	v_pk_mul_f32 v[104:105], v[94:95], v[100:101] op_sel_hi:[1,0]
	v_exp_f32_e32 v102, v102
	v_exp_f32_e32 v104, v104
	v_exp_f32_e32 v103, v103
	v_exp_f32_e32 v105, v105
	v_pk_mul_f32 v[98:99], v[98:99], v[110:111]
	v_pk_mul_f32 v[90:91], v[94:95], v[90:91]
	v_cvt_pk_bf16_f32 v108, v98, v99
	v_or_b32_e32 v98, 16, v156
	v_pk_add_f32 v[102:103], v[102:103], 1.0 op_sel_hi:[1,0]
	v_pk_add_f32 v[104:105], v[104:105], 1.0 op_sel_hi:[1,0]
	v_mad_i64_i32 v[98:99], s[64:65], v98, s85, v[114:115]
	v_rcp_f32_e32 v104, v104
	v_rcp_f32_e32 v105, v105
	v_rcp_f32_e32 v102, v102
	v_rcp_f32_e32 v103, v103
	v_pk_mul_f32 v[94:95], v[88:89], v[100:101] op_sel_hi:[1,0]
	v_lshl_add_u64 v[98:99], v[98:99], 0, v[116:117]
	v_exp_f32_e32 v94, v94
	v_exp_f32_e32 v95, v95
	global_store_dwordx4 v[98:99], v[106:109], off
	v_mul_f32_e32 v98, v159, v159
	v_pk_mul_f32 v[92:93], v[96:97], v[92:93]
	v_pk_mul_f32 v[90:91], v[90:91], v[98:99] op_sel_hi:[1,0]
	v_pk_mul_f32 v[92:93], v[92:93], v[98:99] op_sel_hi:[1,0]
	v_pk_mul_f32 v[90:91], v[90:91], v[104:105]
	v_pk_mul_f32 v[92:93], v[92:93], v[102:103]
	v_cvt_pk_bf16_f32 v90, v90, v91
	v_cvt_pk_bf16_f32 v91, v92, v93
	v_pk_add_f32 v[92:93], v[94:95], 1.0 op_sel_hi:[1,0]
	v_pk_mul_f32 v[96:97], v[86:87], v[100:101] op_sel_hi:[1,0]
	v_rcp_f32_e32 v92, v92
	v_rcp_f32_e32 v93, v93
	v_exp_f32_e32 v96, v96
	v_exp_f32_e32 v97, v97
	v_pk_mul_f32 v[84:85], v[88:89], v[84:85]
	v_pk_mul_f32 v[82:83], v[86:87], v[82:83]
	v_pk_mul_f32 v[84:85], v[84:85], v[98:99] op_sel_hi:[1,0]
	v_pk_add_f32 v[94:95], v[96:97], 1.0 op_sel_hi:[1,0]
	v_pk_mul_f32 v[84:85], v[84:85], v[92:93]
	v_rcp_f32_e32 v94, v94
	v_cvt_pk_bf16_f32 v93, v84, v85
	v_mul_f32_e32 v84, 0xbfb8aa3b, v172
	v_rcp_f32_e32 v95, v95
	v_pk_mul_f32 v[86:87], v[80:81], v[84:85] op_sel_hi:[1,0]
	v_pk_mul_f32 v[88:89], v[78:79], v[84:85] op_sel_hi:[1,0]
	v_exp_f32_e32 v86, v86
	v_exp_f32_e32 v88, v88
	v_exp_f32_e32 v87, v87
	v_exp_f32_e32 v89, v89
	v_pk_mul_f32 v[82:83], v[82:83], v[98:99] op_sel_hi:[1,0]
	v_pk_mul_f32 v[76:77], v[80:81], v[76:77]
	v_pk_mul_f32 v[82:83], v[82:83], v[94:95]
	v_pk_add_f32 v[86:87], v[86:87], 1.0 op_sel_hi:[1,0]
	v_cvt_pk_bf16_f32 v92, v82, v83
	v_or_b32_e32 v82, 32, v156
	v_pk_add_f32 v[88:89], v[88:89], 1.0 op_sel_hi:[1,0]
	v_mad_i64_i32 v[82:83], s[64:65], v82, s85, v[114:115]
	v_rcp_f32_e32 v88, v88
	v_rcp_f32_e32 v89, v89
	v_rcp_f32_e32 v86, v86
	v_rcp_f32_e32 v87, v87
	v_pk_mul_f32 v[74:75], v[78:79], v[74:75]
	v_pk_mul_f32 v[78:79], v[72:73], v[84:85] op_sel_hi:[1,0]
	v_pk_mul_f32 v[80:81], v[70:71], v[84:85] op_sel_hi:[1,0]
	v_lshl_add_u64 v[82:83], v[82:83], 0, v[116:117]
	v_exp_f32_e32 v80, v80
	v_exp_f32_e32 v78, v78
	v_exp_f32_e32 v79, v79
	v_exp_f32_e32 v81, v81
; __device__ __forceinline__ f32x4 sig_from_negl2(f32x4 t) { return rcp_4(exp2_4(t) + 1.0f); }
; __device__ __forceinline__ u32x2 pack4(f32x4 v) { u32x2 w; w.x = cvtpk(v[0], v[1]); w.y = cvtpk(v[2], v[3]); return w; }
;     __device__ __forceinline__ void operator()(const Acc& acc, const Unit& u, int wr, int wc, int fr, int fq) const {
;     ...
;             for (int m = 0; m < 4; ++m) {
;                 const int r = u.pm * 256 + ai * 128 + wr * 64 + m * 16 + fr;
;                 const float rs = rsv[ai][m], nrs = -LOG2E * rs, rs2 = rs * rs;
;                 u32x4 w;
; #pragma unroll
;                 for (int n = 0; n < 2; ++n) {
;                     const f32x4 ga = acc[ai][0][m][n], ua = acc[ai][1][m][n];
;                     const f32x4 sg = sig_from_negl2(ga * nrs);
;                     const u32x2 pk = pack4((ga * ua) * rs2 * sg);
;                     if (n == 0) { w.x = pk.x; w.y = pk.y; } else { w.z = pk.x; w.w = pk.y; }
;                 }
;                 *(u32x4*)(O + (size_t)r * DFF + col) = w;
;             }
	global_store_dwordx4 v[82:83], v[90:93], off
	v_mul_f32_e32 v82, v172, v172
	v_pk_mul_f32 v[74:75], v[74:75], v[82:83] op_sel_hi:[1,0]
	v_pk_mul_f32 v[76:77], v[76:77], v[82:83] op_sel_hi:[1,0]
	v_pk_mul_f32 v[74:75], v[74:75], v[88:89]
	v_pk_mul_f32 v[76:77], v[76:77], v[86:87]
	v_cvt_pk_bf16_f32 v74, v74, v75
	v_cvt_pk_bf16_f32 v75, v76, v77
	v_pk_add_f32 v[76:77], v[78:79], 1.0 op_sel_hi:[1,0]
	v_pk_add_f32 v[78:79], v[80:81], 1.0 op_sel_hi:[1,0]
	v_rcp_f32_e32 v76, v76
	v_rcp_f32_e32 v78, v78
	v_rcp_f32_e32 v79, v79
	v_rcp_f32_e32 v77, v77
	v_pk_mul_f32 v[66:67], v[70:71], v[66:67]
	v_pk_mul_f32 v[68:69], v[72:73], v[68:69]
	v_pk_mul_f32 v[66:67], v[66:67], v[82:83] op_sel_hi:[1,0]
	v_pk_mul_f32 v[68:69], v[68:69], v[82:83] op_sel_hi:[1,0]
	v_pk_mul_f32 v[66:67], v[66:67], v[78:79]
	v_pk_mul_f32 v[68:69], v[68:69], v[76:77]
	v_cvt_pk_bf16_f32 v76, v66, v67
	v_or_b32_e32 v66, 48, v156
	v_mad_i64_i32 v[66:67], s[64:65], v66, s85, v[114:115]
	v_cvt_pk_bf16_f32 v77, v68, v69
	v_lshl_add_u64 v[66:67], v[66:67], 0, v[116:117]
	global_store_dwordx4 v[66:67], v[74:77], off
	v_mul_f32_e32 v66, 0xbfb8aa3b, v161
	v_pk_mul_f32 v[68:69], v[64:65], v[66:67] op_sel_hi:[1,0]
	v_pk_mul_f32 v[70:71], v[62:63], v[66:67] op_sel_hi:[1,0]
	v_exp_f32_e32 v68, v68
	v_exp_f32_e32 v70, v70
	v_exp_f32_e32 v69, v69
	v_exp_f32_e32 v71, v71
	v_add_u32_e32 v67, 0x80, v156
	v_pk_mul_f32 v[58:59], v[62:63], v[58:59]
	v_pk_add_f32 v[68:69], v[68:69], 1.0 op_sel_hi:[1,0]
	v_pk_add_f32 v[70:71], v[70:71], 1.0 op_sel_hi:[1,0]
	v_rcp_f32_e32 v68, v68
	v_rcp_f32_e32 v70, v70
	v_rcp_f32_e32 v71, v71
	v_rcp_f32_e32 v69, v69
	v_pk_mul_f32 v[62:63], v[56:57], v[66:67] op_sel_hi:[1,0]
	v_mul_f32_e32 v72, v161, v161
	v_exp_f32_e32 v62, v62
	v_exp_f32_e32 v63, v63
	v_pk_mul_f32 v[60:61], v[64:65], v[60:61]
	v_pk_mul_f32 v[58:59], v[58:59], v[72:73] op_sel_hi:[1,0]
	v_pk_mul_f32 v[60:61], v[60:61], v[72:73] op_sel_hi:[1,0]
	v_pk_mul_f32 v[58:59], v[58:59], v[70:71]
	v_pk_mul_f32 v[60:61], v[60:61], v[68:69]
	v_cvt_pk_bf16_f32 v58, v58, v59
	v_cvt_pk_bf16_f32 v59, v60, v61
	v_pk_add_f32 v[60:61], v[62:63], 1.0 op_sel_hi:[1,0]
	v_pk_mul_f32 v[64:65], v[54:55], v[66:67] op_sel_hi:[1,0]
	v_rcp_f32_e32 v60, v60
	v_rcp_f32_e32 v61, v61
	v_exp_f32_e32 v64, v64
	v_exp_f32_e32 v65, v65
	v_pk_mul_f32 v[52:53], v[56:57], v[52:53]
	v_pk_mul_f32 v[50:51], v[54:55], v[50:51]
	v_pk_mul_f32 v[52:53], v[52:53], v[72:73] op_sel_hi:[1,0]
	v_pk_add_f32 v[62:63], v[64:65], 1.0 op_sel_hi:[1,0]
	v_pk_mul_f32 v[52:53], v[52:53], v[60:61]
	v_rcp_f32_e32 v62, v62
	v_cvt_pk_bf16_f32 v61, v52, v53
	v_mul_f32_e32 v52, 0xbfb8aa3b, v173
	v_pk_mul_f32 v[54:55], v[48:49], v[52:53] op_sel_hi:[1,0]
	v_pk_mul_f32 v[56:57], v[46:47], v[52:53] op_sel_hi:[1,0]
	v_rcp_f32_e32 v63, v63
	v_exp_f32_e32 v56, v56
	v_exp_f32_e32 v54, v54
	v_exp_f32_e32 v55, v55
	v_exp_f32_e32 v57, v57
	v_pk_mul_f32 v[50:51], v[50:51], v[72:73] op_sel_hi:[1,0]
	v_pk_mul_f32 v[42:43], v[46:47], v[42:43]
	v_pk_mul_f32 v[50:51], v[50:51], v[62:63]
	v_pk_add_f32 v[54:55], v[54:55], 1.0 op_sel_hi:[1,0]
	v_pk_add_f32 v[56:57], v[56:57], 1.0 op_sel_hi:[1,0]
	v_cvt_pk_bf16_f32 v60, v50, v51
	v_mad_i64_i32 v[50:51], s[64:65], v67, s85, v[114:115]
	v_rcp_f32_e32 v56, v56
	v_rcp_f32_e32 v57, v57
	v_rcp_f32_e32 v54, v54
	v_rcp_f32_e32 v55, v55
	v_pk_mul_f32 v[46:47], v[40:41], v[52:53] op_sel_hi:[1,0]
	v_lshl_add_u64 v[50:51], v[50:51], 0, v[116:117]
	v_exp_f32_e32 v46, v46
	v_exp_f32_e32 v47, v47
	global_store_dwordx4 v[50:51], v[58:61], off
	v_mul_f32_e32 v50, v173, v173
	v_pk_mul_f32 v[44:45], v[48:49], v[44:45]
	v_pk_mul_f32 v[42:43], v[42:43], v[50:51] op_sel_hi:[1,0]
	v_pk_mul_f32 v[44:45], v[44:45], v[50:51] op_sel_hi:[1,0]
	v_pk_mul_f32 v[42:43], v[42:43], v[56:57]
	v_pk_mul_f32 v[44:45], v[44:45], v[54:55]
	v_cvt_pk_bf16_f32 v42, v42, v43
	v_cvt_pk_bf16_f32 v43, v44, v45
	v_pk_add_f32 v[44:45], v[46:47], 1.0 op_sel_hi:[1,0]
	v_fmamk_f32 v158, v158, 0x3a800000, v155
	v_pk_mul_f32 v[48:49], v[38:39], v[52:53] op_sel_hi:[1,0]
	v_rcp_f32_e32 v44, v44
	v_rcp_f32_e32 v45, v45
	v_rsq_f32_e32 v158, v158
	v_exp_f32_e32 v48, v48
	v_exp_f32_e32 v49, v49
	v_pk_mul_f32 v[36:37], v[40:41], v[36:37]
	v_pk_mul_f32 v[34:35], v[38:39], v[34:35]
	v_pk_mul_f32 v[36:37], v[36:37], v[50:51] op_sel_hi:[1,0]
	v_pk_add_f32 v[46:47], v[48:49], 1.0 op_sel_hi:[1,0]
	v_pk_mul_f32 v[36:37], v[36:37], v[44:45]
	v_rcp_f32_e32 v46, v46
	v_cvt_pk_bf16_f32 v45, v36, v37
	v_mul_f32_e32 v36, 0xbfb8aa3b, v158
	v_rcp_f32_e32 v47, v47
	v_pk_mul_f32 v[38:39], v[32:33], v[36:37] op_sel_hi:[1,0]
; __device__ __forceinline__ f32x4 sig_from_negl2(f32x4 t) { return rcp_4(exp2_4(t) + 1.0f); }
; __device__ __forceinline__ u32x2 pack4(f32x4 v) { u32x2 w; w.x = cvtpk(v[0], v[1]); w.y = cvtpk(v[2], v[3]); return w; }
; #define PG8_BAR __builtin_amdgcn_s_barrier()
; #define PG8_STATS(pm_) do { if constexpr (Epi::STAB) { if (wr == 1) { const char* _sb = (const char*)E.st + (size_t)(pm_) * 16384 + (size_t)lane * 16; \
;         _Pragma("unroll") for (int _i = 0; _i < 4; ++_i) __builtin_amdgcn_global_load_lds((const unsigned*)(_sb + ((wid - 4) + 4 * _i) * 1024), (LAS unsigned*)(lds + STAB_OFF + ((wid - 4) + 4 * _i) * 1024), 16, 0, 0); } } } while (0)
; template <class Epi>
; __device__ __forceinline__ void gemm_phase(LAS unsigned char* lds, const Gemm g, const StaticOrder& S, const Epi& E) {
;     ...
;         if (!has_next) break;
; #pragma unroll
;         for (int a = 0; a < 2; ++a)
; #pragma unroll
;             for (int b = 0; b < 2; ++b)
; #pragma unroll
;                 for (int m = 0; m < 4; ++m)
; #pragma unroll
;                     for (int n = 0; n < 2; ++n) acc[a][b][m][n] = (f32x4){0.f, 0.f, 0.f, 0.f};
;         cur = nxt; cA = nA; cB = nB; ++ui;
;         if (wr == 1) PG8_BAR;
;         PG8_STATS(cur.pm);
;     __device__ __forceinline__ void operator()(const Acc& acc, const Unit& u, int wr, int wc, int fr, int fq) const {
;     ...
;             for (int m = 0; m < 4; ++m) {
;                 const int r = u.pm * 256 + ai * 128 + wr * 64 + m * 16 + fr;
;                 const float rs = rsv[ai][m], nrs = -LOG2E * rs, rs2 = rs * rs;
;                 u32x4 w;
; #pragma unroll
;                 for (int n = 0; n < 2; ++n) {
;                     const f32x4 ga = acc[ai][0][m][n], ua = acc[ai][1][m][n];
;                     const f32x4 sg = sig_from_negl2(ga * nrs);
;                     const u32x2 pk = pack4((ga * ua) * rs2 * sg);
;                     if (n == 0) { w.x = pk.x; w.y = pk.y; } else { w.z = pk.x; w.w = pk.y; }
;                 }
;                 *(u32x4*)(O + (size_t)r * DFF + col) = w;
;             }
	v_pk_mul_f32 v[40:41], v[30:31], v[36:37] op_sel_hi:[1,0]
	v_exp_f32_e32 v38, v38
	v_exp_f32_e32 v40, v40
	v_exp_f32_e32 v39, v39
	v_exp_f32_e32 v41, v41
	v_pk_mul_f32 v[34:35], v[34:35], v[50:51] op_sel_hi:[1,0]
	v_pk_mul_f32 v[26:27], v[30:31], v[26:27]
	v_pk_mul_f32 v[34:35], v[34:35], v[46:47]
	v_pk_add_f32 v[38:39], v[38:39], 1.0 op_sel_hi:[1,0]
	v_cvt_pk_bf16_f32 v44, v34, v35
	v_add_u32_e32 v34, 0x90, v156
	v_pk_add_f32 v[40:41], v[40:41], 1.0 op_sel_hi:[1,0]
	v_mad_i64_i32 v[34:35], s[64:65], v34, s85, v[114:115]
	v_rcp_f32_e32 v40, v40
	v_rcp_f32_e32 v41, v41
	v_rcp_f32_e32 v38, v38
	v_rcp_f32_e32 v39, v39
	v_pk_mul_f32 v[30:31], v[24:25], v[36:37] op_sel_hi:[1,0]
	v_lshl_add_u64 v[34:35], v[34:35], 0, v[116:117]
	v_exp_f32_e32 v30, v30
	v_exp_f32_e32 v31, v31
	global_store_dwordx4 v[34:35], v[42:45], off
	v_mul_f32_e32 v34, v158, v158
	v_pk_mul_f32 v[28:29], v[32:33], v[28:29]
	v_pk_mul_f32 v[26:27], v[26:27], v[34:35] op_sel_hi:[1,0]
	v_pk_mul_f32 v[28:29], v[28:29], v[34:35] op_sel_hi:[1,0]
	v_pk_mul_f32 v[26:27], v[26:27], v[40:41]
	v_pk_mul_f32 v[28:29], v[28:29], v[38:39]
	v_cvt_pk_bf16_f32 v26, v26, v27
	v_cvt_pk_bf16_f32 v27, v28, v29
	v_pk_add_f32 v[28:29], v[30:31], 1.0 op_sel_hi:[1,0]
	v_pk_mul_f32 v[32:33], v[22:23], v[36:37] op_sel_hi:[1,0]
	v_rcp_f32_e32 v28, v28
	v_rcp_f32_e32 v29, v29
	v_exp_f32_e32 v32, v32
	v_exp_f32_e32 v33, v33
	v_pk_mul_f32 v[20:21], v[24:25], v[20:21]
	v_pk_mul_f32 v[18:19], v[22:23], v[18:19]
	v_pk_mul_f32 v[20:21], v[20:21], v[34:35] op_sel_hi:[1,0]
	v_pk_add_f32 v[30:31], v[32:33], 1.0 op_sel_hi:[1,0]
	v_pk_mul_f32 v[20:21], v[20:21], v[28:29]
	v_rcp_f32_e32 v30, v30
	v_cvt_pk_bf16_f32 v29, v20, v21
	v_mul_f32_e32 v20, 0xbfb8aa3b, v157
	v_rcp_f32_e32 v31, v31
	v_pk_mul_f32 v[22:23], v[16:17], v[20:21] op_sel_hi:[1,0]
	v_pk_mul_f32 v[24:25], v[14:15], v[20:21] op_sel_hi:[1,0]
	v_exp_f32_e32 v22, v22
	v_exp_f32_e32 v24, v24
	v_exp_f32_e32 v23, v23
	v_exp_f32_e32 v25, v25
	v_pk_mul_f32 v[18:19], v[18:19], v[34:35] op_sel_hi:[1,0]
	v_pk_mul_f32 v[12:13], v[16:17], v[12:13]
	v_pk_mul_f32 v[18:19], v[18:19], v[30:31]
	v_pk_add_f32 v[22:23], v[22:23], 1.0 op_sel_hi:[1,0]
	v_cvt_pk_bf16_f32 v28, v18, v19
	v_add_u32_e32 v18, 0xa0, v156
	v_pk_add_f32 v[24:25], v[24:25], 1.0 op_sel_hi:[1,0]
	v_mad_i64_i32 v[18:19], s[64:65], v18, s85, v[114:115]
	v_rcp_f32_e32 v24, v24
	v_rcp_f32_e32 v25, v25
	v_rcp_f32_e32 v22, v22
	v_rcp_f32_e32 v23, v23
	v_pk_mul_f32 v[10:11], v[14:15], v[10:11]
	v_pk_mul_f32 v[14:15], v[8:9], v[20:21] op_sel_hi:[1,0]
	v_pk_mul_f32 v[16:17], v[6:7], v[20:21] op_sel_hi:[1,0]
	v_lshl_add_u64 v[18:19], v[18:19], 0, v[116:117]
	v_exp_f32_e32 v16, v16
	v_exp_f32_e32 v14, v14
	v_exp_f32_e32 v15, v15
	v_exp_f32_e32 v17, v17
	global_store_dwordx4 v[18:19], v[26:29], off
	v_mul_f32_e32 v18, v157, v157
	v_pk_mul_f32 v[10:11], v[10:11], v[18:19] op_sel_hi:[1,0]
	v_pk_mul_f32 v[12:13], v[12:13], v[18:19] op_sel_hi:[1,0]
	v_pk_mul_f32 v[10:11], v[10:11], v[24:25]
	v_pk_mul_f32 v[12:13], v[12:13], v[22:23]
	v_cvt_pk_bf16_f32 v10, v10, v11
	v_cvt_pk_bf16_f32 v11, v12, v13
	v_pk_add_f32 v[12:13], v[14:15], 1.0 op_sel_hi:[1,0]
	v_pk_add_f32 v[14:15], v[16:17], 1.0 op_sel_hi:[1,0]
	v_rcp_f32_e32 v12, v12
	v_rcp_f32_e32 v14, v14
	v_rcp_f32_e32 v15, v15
	v_rcp_f32_e32 v13, v13
	v_pk_mul_f32 v[2:3], v[6:7], v[2:3]
	v_pk_mul_f32 v[4:5], v[8:9], v[4:5]
	v_pk_mul_f32 v[2:3], v[2:3], v[18:19] op_sel_hi:[1,0]
	v_pk_mul_f32 v[4:5], v[4:5], v[18:19] op_sel_hi:[1,0]
	v_pk_mul_f32 v[2:3], v[2:3], v[14:15]
	v_pk_mul_f32 v[4:5], v[4:5], v[12:13]
	v_cvt_pk_bf16_f32 v12, v2, v3
	v_add_u32_e32 v2, 0xb0, v156
	v_mad_i64_i32 v[2:3], s[64:65], v2, s85, v[114:115]
	v_cvt_pk_bf16_f32 v13, v4, v5
	v_lshl_add_u64 v[2:3], v[2:3], 0, v[116:117]
	s_andn2_b64 vcc, exec, s[2:3]
	s_mov_b64 s[2:3], -1
	global_store_dwordx4 v[2:3], v[10:13], off
	s_cbranch_vccnz .LBB0_130
	s_and_b64 vcc, exec, s[0:1]
	s_cbranch_vccnz .LBB0_129
	s_lshl_b64 s[2:3], s[48:49], 14
	v_lshl_add_u64 v[2:3], v[138:139], 0, s[2:3]
	s_add_i32 s2, 0, 0x20400
	v_lshl_add_u64 v[4:5], v[2:3], 0, s[36:37]
	s_add_i32 m0, s2, s36
	s_barrier
	global_load_lds_dwordx4 v[4:5], off
	v_lshl_add_u64 v[4:5], v[2:3], 0, s[6:7]
	s_add_i32 m0, s2, s6
	s_nop 0
	global_load_lds_dwordx4 v[4:5], off
	v_lshl_add_u64 v[4:5], v[2:3], 0, s[42:43]
	s_add_i32 m0, s2, s42
	v_lshl_add_u64 v[2:3], v[2:3], 0, s[44:45]
	global_load_lds_dwordx4 v[4:5], off
	s_add_i32 m0, s2, s44
	s_nop 0
	global_load_lds_dwordx4 v[2:3], off
	s_branch .LBB0_129

; #define LAS __attribute__((address_space(3)))
; __device__ __forceinline__ f32x4 sig_from_negl2(f32x4 t) { return rcp_4(exp2_4(t) + 1.0f); }
; __device__ __forceinline__ u32x2 pack4(f32x4 v) { u32x2 w; w.x = cvtpk(v[0], v[1]); w.y = cvtpk(v[2], v[3]); return w; }
; __device__ __forceinline__ void rstd8_lds(int rrel, int fq, float inv_dim, float (&rs)[2][4]) {
;     const LAS unsigned char* lds = (const LAS unsigned char*)0;
;     f32x4 v[2][4];
; #pragma unroll
;     for (int ai = 0; ai < 2; ++ai)
; #pragma unroll
;         for (int m = 0; m < 4; ++m) v[ai][m] = *(const LAS f32x4*)(lds + STAB_OFF + (rrel + ai * 128 + m * 16) * 64 + fq * 16);
; #pragma unroll
;     for (int ai = 0; ai < 2; ++ai)
; #pragma unroll
;         for (int m = 0; m < 4; ++m) { float q = (v[ai][m][0] + v[ai][m][1]) + (v[ai][m][2] + v[ai][m][3]); q += __shfl_xor(q, 16); q += __shfl_xor(q, 32); rs[ai][m] = __builtin_amdgcn_rsqf(q * inv_dim + EPS); }
; }
;     __device__ __forceinline__ void operator()(const Acc& acc, const Unit& u, int wr, int wc, int fr, int fq) const {
;         const int col = u.pn * 128 + wc * 32 + fq * 8;
;         float rsv[2][4]; rstd8_lds(wr * 64 + fr, fq, 1.0f / 1024.0f, rsv);
; #pragma unroll
;         for (int ai = 0; ai < 2; ++ai)
; #pragma unroll
;             for (int m = 0; m < 4; ++m) {
;                 const int r = u.pm * 256 + ai * 128 + wr * 64 + m * 16 + fr;
;                 const float rs = rsv[ai][m], nrs = -LOG2E * rs, rs2 = rs * rs;
;                 u32x4 w;
; #pragma unroll
;                 for (int n = 0; n < 2; ++n) {
;                     const f32x4 ga = acc[ai][0][m][n], ua = acc[ai][1][m][n];
;                     const f32x4 sg = sig_from_negl2(ga * nrs);
;                     const u32x2 pk = pack4((ga * ua) * rs2 * sg);
;                     if (n == 0) { w.x = pk.x; w.y = pk.y; } else { w.z = pk.x; w.w = pk.y; }
;                 }
;                 *(u32x4*)(O + (size_t)r * DFF + col) = w;
;             }
.LBB0_887:
	ds_read_b128 v[156:159], v153
	ds_read_b128 v[160:163], v153 offset:1024
	ds_read_b128 v[164:167], v153 offset:2048
	ds_read_b128 v[172:175], v153 offset:3072
	v_and_b32_e32 v176, 64, v154
	v_xor_b32_e32 v169, 16, v154
	v_add_u32_e32 v178, 64, v176
	v_cmp_lt_i32_e32 vcc, v169, v178
	s_waitcnt lgkmcnt(0)
	v_mov_b32_e32 v176, v157
	v_mov_b32_e32 v177, v158
	v_mov_b32_e32 v157, v159
	v_cndmask_b32_e32 v169, v154, v169, vcc
	v_pk_add_f32 v[156:157], v[176:177], v[156:157]
	v_lshlrev_b32_e32 v169, 2, v169
	v_add_f32_e32 v156, v156, v157
	v_xor_b32_e32 v158, 32, v154
	v_cmp_lt_i32_e32 vcc, v158, v178
	v_pk_mul_f32 v[124:125], v[128:129], v[124:125]
	v_pk_mul_f32 v[122:123], v[126:127], v[122:123]
	v_cndmask_b32_e32 v158, v154, v158, vcc
	v_lshlrev_b32_e32 v190, 2, v158
	s_waitcnt lgkmcnt(0)
	v_mov_b32_e32 v247, v156
	v_mov_b32_e32 v157, v156
	s_nop 1
	v_permlane16_swap_b32_e32 v157, v247
	v_add_f32_e32 v188, v157, v247
	ds_read_b128 v[156:159], v153 offset:8192
	ds_read_b128 v[176:179], v153 offset:9216
	ds_read_b128 v[180:183], v153 offset:10240
	ds_read_b128 v[184:187], v153 offset:11264
	v_pk_mul_f32 v[114:115], v[118:119], v[114:115]
	v_pk_mul_f32 v[116:117], v[120:121], v[116:117]
	v_lshl_or_b32 v168, s42, 7, v149
	s_waitcnt lgkmcnt(0)
	v_mov_b32_e32 v247, v188
	v_mov_b32_e32 v189, v188
	s_nop 1
	v_permlane32_swap_b32_e32 v189, v247
	v_add_f32_e32 v191, v189, v247
	v_mov_b32_e32 v188, v161
	v_mov_b32_e32 v189, v162
	v_mov_b32_e32 v161, v163
	v_pk_add_f32 v[160:161], v[188:189], v[160:161]
	v_pk_mul_f32 v[106:107], v[110:111], v[106:107]
	v_add_f32_e32 v162, v160, v161
	v_mov_b32_e32 v160, v165
	v_mov_b32_e32 v161, v166
	v_mov_b32_e32 v165, v167
	v_pk_add_f32 v[160:161], v[160:161], v[164:165]
	v_add_f32_e32 v160, v160, v161
	v_fmamk_f32 v164, v191, 0x3a800000, v155
	v_rsq_f32_e32 v166, v164
	s_waitcnt lgkmcnt(0)
	v_mov_b32_e32 v247, v162
	v_mov_b32_e32 v163, v162
	s_nop 1
	v_permlane16_swap_b32_e32 v163, v247
	v_add_f32_e32 v162, v163, v247
	v_mov_b32_e32 v247, v160
	v_mov_b32_e32 v161, v160
	s_nop 1
	v_permlane16_swap_b32_e32 v161, v247
	v_add_f32_e32 v164, v161, v247
	v_mov_b32_e32 v160, v173
	v_mov_b32_e32 v161, v174
	v_mov_b32_e32 v173, v175
	v_pk_add_f32 v[160:161], v[160:161], v[172:173]
	s_waitcnt lgkmcnt(0)
	v_mov_b32_e32 v247, v162
	v_mov_b32_e32 v163, v162
	s_nop 1
	v_permlane32_swap_b32_e32 v163, v247
	v_add_f32_e32 v162, v163, v247
	v_add_f32_e32 v160, v160, v161
	v_fmamk_f32 v162, v162, 0x3a800000, v155
	v_rsq_f32_e32 v167, v162
	v_pk_mul_f32 v[108:109], v[112:113], v[108:109]
	s_waitcnt lgkmcnt(0)
	v_mov_b32_e32 v247, v160
	v_mov_b32_e32 v161, v160
	s_nop 1
	v_permlane16_swap_b32_e32 v161, v247
	v_add_f32_e32 v163, v161, v247
	v_mov_b32_e32 v160, v157
	v_mov_b32_e32 v161, v158
	v_mov_b32_e32 v157, v159
	v_pk_add_f32 v[156:157], v[160:161], v[156:157]
	v_mov_b32_e32 v247, v164
	v_mov_b32_e32 v165, v164
	s_nop 1
	v_permlane32_swap_b32_e32 v165, v247
	v_add_f32_e32 v162, v165, v247
	v_add_f32_e32 v156, v156, v157
	v_fmamk_f32 v158, v162, 0x3a800000, v155
	v_rsq_f32_e32 v159, v158
	v_pk_mul_f32 v[100:101], v[104:105], v[100:101]
	s_waitcnt lgkmcnt(0)
	v_mov_b32_e32 v247, v156
	v_mov_b32_e32 v157, v156
	s_nop 1
	v_permlane16_swap_b32_e32 v157, v247
	v_add_f32_e32 v160, v157, v247
	v_mov_b32_e32 v156, v177
	v_mov_b32_e32 v157, v178
	v_mov_b32_e32 v177, v179
	v_pk_add_f32 v[156:157], v[156:157], v[176:177]
	v_mov_b32_e32 v247, v163
	v_mov_b32_e32 v164, v163
	s_nop 1
	v_permlane32_swap_b32_e32 v164, v247
	v_add_f32_e32 v158, v164, v247
	v_add_f32_e32 v156, v156, v157
	v_fmamk_f32 v158, v158, 0x3a800000, v155
	v_rsq_f32_e32 v172, v158
	s_waitcnt lgkmcnt(0)
	v_mov_b32_e32 v247, v160
	v_mov_b32_e32 v161, v160
	s_nop 1
	v_permlane32_swap_b32_e32 v161, v247
	v_add_f32_e32 v158, v161, v247
	v_fmamk_f32 v158, v158, 0x3a800000, v155
	v_rsq_f32_e32 v161, v158
	v_mov_b32_e32 v247, v156
	v_mov_b32_e32 v157, v156
	s_nop 1
	v_permlane16_swap_b32_e32 v157, v247
	v_add_f32_e32 v158, v157, v247
	v_mov_b32_e32 v156, v181
	v_mov_b32_e32 v157, v182
	v_mov_b32_e32 v181, v183
	v_pk_add_f32 v[156:157], v[156:157], v[180:181]
	v_add_f32_e32 v162, v156, v157
	v_mov_b32_e32 v156, v185
	v_mov_b32_e32 v157, v186
	s_waitcnt lgkmcnt(0)
	v_mov_b32_e32 v247, v158
	v_mov_b32_e32 v160, v158
	s_nop 1
	v_permlane32_swap_b32_e32 v160, v247
	v_add_f32_e32 v158, v160, v247
	v_fmamk_f32 v158, v158, 0x3a800000, v155
	v_mov_b32_e32 v247, v162
	v_mov_b32_e32 v163, v162
	s_nop 1
	v_permlane16_swap_b32_e32 v163, v247
	v_add_f32_e32 v160, v163, v247
	v_rsq_f32_e32 v173, v158
	v_mov_b32_e32 v185, v187
	v_pk_add_f32 v[156:157], v[156:157], v[184:185]
	v_pk_mul_f32 v[98:99], v[102:103], v[98:99]
	s_waitcnt lgkmcnt(0)
	v_mov_b32_e32 v247, v160
	v_mov_b32_e32 v162, v160
	s_nop 1
	v_permlane32_swap_b32_e32 v162, v247
	v_add_f32_e32 v158, v162, v247
	v_mul_f32_e32 v160, 0xbfb8aa3b, v166
	v_pk_mul_f32 v[162:163], v[128:129], v[160:161] op_sel_hi:[1,0]
	v_pk_mul_f32 v[164:165], v[126:127], v[160:161] op_sel_hi:[1,0]
	v_exp_f32_e32 v162, v162
	v_exp_f32_e32 v164, v164
	v_exp_f32_e32 v163, v163
	v_exp_f32_e32 v165, v165
	v_add_f32_e32 v156, v156, v157
	v_pk_add_f32 v[162:163], v[162:163], 1.0 op_sel_hi:[1,0]
	v_pk_add_f32 v[164:165], v[164:165], 1.0 op_sel_hi:[1,0]
	v_rcp_f32_e32 v162, v162
	v_rcp_f32_e32 v164, v164
	v_rcp_f32_e32 v165, v165
	v_rcp_f32_e32 v163, v163
	v_pk_mul_f32 v[126:127], v[120:121], v[160:161] op_sel_hi:[1,0]
	v_pk_mul_f32 v[128:129], v[118:119], v[160:161] op_sel_hi:[1,0]
	v_exp_f32_e32 v126, v126
	v_exp_f32_e32 v128, v128
	v_exp_f32_e32 v127, v127
	v_exp_f32_e32 v129, v129
	v_mul_f32_e32 v166, v166, v166
	v_pk_mul_f32 v[122:123], v[122:123], v[166:167] op_sel_hi:[1,0]
	v_pk_mul_f32 v[124:125], v[124:125], v[166:167] op_sel_hi:[1,0]
	s_waitcnt lgkmcnt(0)
; __device__ __forceinline__ f32x4 sig_from_negl2(f32x4 t) { return rcp_4(exp2_4(t) + 1.0f); }
; __device__ __forceinline__ u32x2 pack4(f32x4 v) { u32x2 w; w.x = cvtpk(v[0], v[1]); w.y = cvtpk(v[2], v[3]); return w; }
; __device__ __forceinline__ void rstd8_lds(int rrel, int fq, float inv_dim, float (&rs)[2][4]) {
;     ...
;         for (int m = 0; m < 4; ++m) { float q = (v[ai][m][0] + v[ai][m][1]) + (v[ai][m][2] + v[ai][m][3]); q += __shfl_xor(q, 16); q += __shfl_xor(q, 32); rs[ai][m] = __builtin_amdgcn_rsqf(q * inv_dim + EPS); }
;     __device__ __forceinline__ void operator()(const Acc& acc, const Unit& u, int wr, int wc, int fr, int fq) const {
;     ...
;             for (int m = 0; m < 4; ++m) {
;                 const int r = u.pm * 256 + ai * 128 + wr * 64 + m * 16 + fr;
;                 const float rs = rsv[ai][m], nrs = -LOG2E * rs, rs2 = rs * rs;
;                 u32x4 w;
; #pragma unroll
;                 for (int n = 0; n < 2; ++n) {
;                     const f32x4 ga = acc[ai][0][m][n], ua = acc[ai][1][m][n];
;                     const f32x4 sg = sig_from_negl2(ga * nrs);
;                     const u32x2 pk = pack4((ga * ua) * rs2 * sg);
;                     if (n == 0) { w.x = pk.x; w.y = pk.y; } else { w.z = pk.x; w.w = pk.y; }
;                 }
;                 *(u32x4*)(O + (size_t)r * DFF + col) = w;
;             }
	v_mov_b32_e32 v247, v156
	v_mov_b32_e32 v157, v156
	s_nop 1
	v_permlane16_swap_b32_e32 v157, v247
	v_add_f32_e32 v156, v157, v247
	v_pk_mul_f32 v[124:125], v[124:125], v[162:163]
	v_pk_mul_f32 v[122:123], v[122:123], v[164:165]
	v_cvt_pk_bf16_f32 v122, v122, v123
	v_cvt_pk_bf16_f32 v123, v124, v125
	v_pk_add_f32 v[124:125], v[126:127], 1.0 op_sel_hi:[1,0]
	v_pk_add_f32 v[126:127], v[128:129], 1.0 op_sel_hi:[1,0]
	v_rcp_f32_e32 v124, v124
	v_rcp_f32_e32 v126, v126
	v_rcp_f32_e32 v127, v127
	v_rcp_f32_e32 v125, v125
	v_pk_mul_f32 v[114:115], v[114:115], v[166:167] op_sel_hi:[1,0]
	v_mul_f32_e32 v120, 0xbfb8aa3b, v167
	s_waitcnt lgkmcnt(0)
	v_mov_b32_e32 v247, v156
	v_mov_b32_e32 v157, v156
	s_nop 1
	v_permlane32_swap_b32_e32 v157, v247
	v_add_f32_e32 v156, v157, v247
	v_pk_mul_f32 v[114:115], v[114:115], v[126:127]
	v_pk_mul_f32 v[126:127], v[112:113], v[120:121] op_sel_hi:[1,0]
	v_pk_mul_f32 v[128:129], v[110:111], v[120:121] op_sel_hi:[1,0]
	v_fmamk_f32 v156, v156, 0x3a800000, v155
	v_pk_mul_f32 v[116:117], v[116:117], v[166:167] op_sel_hi:[1,0]
	v_exp_f32_e32 v128, v128
	v_exp_f32_e32 v126, v126
	v_exp_f32_e32 v127, v127
	v_exp_f32_e32 v129, v129
	v_rsq_f32_e32 v157, v156
	v_lshl_add_u32 v156, s40, 8, v1
	v_ashrrev_i32_e32 v169, 31, v168
	v_pk_mul_f32 v[116:117], v[116:117], v[124:125]
	v_cvt_pk_bf16_f32 v124, v114, v115
	v_mov_b64_e32 v[114:115], s[16:17]
	v_cvt_pk_bf16_f32 v125, v116, v117
	v_mad_i64_i32 v[118:119], s[44:45], v156, s60, v[114:115]
	v_lshlrev_b64 v[116:117], 1, v[168:169]
	v_lshl_add_u64 v[118:119], v[118:119], 0, v[116:117]
	global_store_dwordx4 v[118:119], v[122:125], off
	v_pk_mul_f32 v[110:111], v[104:105], v[120:121] op_sel_hi:[1,0]
	v_mul_f32_e32 v118, v167, v167
	v_pk_add_f32 v[122:123], v[126:127], 1.0 op_sel_hi:[1,0]
	v_pk_add_f32 v[124:125], v[128:129], 1.0 op_sel_hi:[1,0]
	v_rcp_f32_e32 v122, v122
	v_rcp_f32_e32 v124, v124
	v_rcp_f32_e32 v125, v125
	v_rcp_f32_e32 v123, v123
	v_exp_f32_e32 v110, v110
	v_exp_f32_e32 v111, v111
	v_pk_mul_f32 v[106:107], v[106:107], v[118:119] op_sel_hi:[1,0]
	v_pk_mul_f32 v[108:109], v[108:109], v[118:119] op_sel_hi:[1,0]
	v_pk_mul_f32 v[106:107], v[106:107], v[124:125]
	v_pk_mul_f32 v[108:109], v[108:109], v[122:123]
	v_cvt_pk_bf16_f32 v106, v106, v107
	v_cvt_pk_bf16_f32 v107, v108, v109
	v_pk_add_f32 v[108:109], v[110:111], 1.0 op_sel_hi:[1,0]
	v_pk_mul_f32 v[112:113], v[102:103], v[120:121] op_sel_hi:[1,0]
	v_rcp_f32_e32 v108, v108
	v_rcp_f32_e32 v109, v109
	v_exp_f32_e32 v112, v112
	v_exp_f32_e32 v113, v113
	v_pk_mul_f32 v[100:101], v[100:101], v[118:119] op_sel_hi:[1,0]
	v_pk_mul_f32 v[98:99], v[98:99], v[118:119] op_sel_hi:[1,0]
	v_pk_mul_f32 v[100:101], v[100:101], v[108:109]
	v_pk_add_f32 v[110:111], v[112:113], 1.0 op_sel_hi:[1,0]
	v_cvt_pk_bf16_f32 v109, v100, v101
	v_mul_f32_e32 v100, 0xbfb8aa3b, v159
	v_rcp_f32_e32 v110, v110
	v_rcp_f32_e32 v111, v111
	v_pk_mul_f32 v[102:103], v[96:97], v[100:101] op_sel_hi:[1,0]
	v_pk_mul_f32 v[104:105], v[94:95], v[100:101] op_sel_hi:[1,0]
	v_exp_f32_e32 v102, v102
	v_exp_f32_e32 v104, v104
	v_exp_f32_e32 v103, v103
	v_exp_f32_e32 v105, v105
	v_pk_mul_f32 v[98:99], v[98:99], v[110:111]
	v_pk_mul_f32 v[90:91], v[94:95], v[90:91]
	v_cvt_pk_bf16_f32 v108, v98, v99
	v_or_b32_e32 v98, 16, v156
	v_pk_add_f32 v[102:103], v[102:103], 1.0 op_sel_hi:[1,0]
	v_pk_add_f32 v[104:105], v[104:105], 1.0 op_sel_hi:[1,0]
	v_mad_i64_i32 v[98:99], s[44:45], v98, s60, v[114:115]
	v_rcp_f32_e32 v104, v104
	v_rcp_f32_e32 v105, v105
	v_rcp_f32_e32 v102, v102
	v_rcp_f32_e32 v103, v103
	v_pk_mul_f32 v[94:95], v[88:89], v[100:101] op_sel_hi:[1,0]
	v_lshl_add_u64 v[98:99], v[98:99], 0, v[116:117]
	v_exp_f32_e32 v94, v94
	v_exp_f32_e32 v95, v95
	global_store_dwordx4 v[98:99], v[106:109], off
	v_mul_f32_e32 v98, v159, v159
	v_pk_mul_f32 v[92:93], v[96:97], v[92:93]
	v_pk_mul_f32 v[90:91], v[90:91], v[98:99] op_sel_hi:[1,0]
	v_pk_mul_f32 v[92:93], v[92:93], v[98:99] op_sel_hi:[1,0]
	v_pk_mul_f32 v[90:91], v[90:91], v[104:105]
	v_pk_mul_f32 v[92:93], v[92:93], v[102:103]
	v_cvt_pk_bf16_f32 v90, v90, v91
	v_cvt_pk_bf16_f32 v91, v92, v93
	v_pk_add_f32 v[92:93], v[94:95], 1.0 op_sel_hi:[1,0]
	v_pk_mul_f32 v[96:97], v[86:87], v[100:101] op_sel_hi:[1,0]
	v_rcp_f32_e32 v92, v92
	v_rcp_f32_e32 v93, v93
	v_exp_f32_e32 v96, v96
	v_exp_f32_e32 v97, v97
	v_pk_mul_f32 v[84:85], v[88:89], v[84:85]
	v_pk_mul_f32 v[82:83], v[86:87], v[82:83]
	v_pk_mul_f32 v[84:85], v[84:85], v[98:99] op_sel_hi:[1,0]
	v_pk_add_f32 v[94:95], v[96:97], 1.0 op_sel_hi:[1,0]
	v_pk_mul_f32 v[84:85], v[84:85], v[92:93]
	v_rcp_f32_e32 v94, v94
	v_cvt_pk_bf16_f32 v93, v84, v85
	v_mul_f32_e32 v84, 0xbfb8aa3b, v172
	v_rcp_f32_e32 v95, v95
	v_pk_mul_f32 v[86:87], v[80:81], v[84:85] op_sel_hi:[1,0]
	v_pk_mul_f32 v[88:89], v[78:79], v[84:85] op_sel_hi:[1,0]
	v_exp_f32_e32 v86, v86
	v_exp_f32_e32 v88, v88
	v_exp_f32_e32 v87, v87
	v_exp_f32_e32 v89, v89
	v_pk_mul_f32 v[82:83], v[82:83], v[98:99] op_sel_hi:[1,0]
	v_pk_mul_f32 v[76:77], v[80:81], v[76:77]
	v_pk_mul_f32 v[82:83], v[82:83], v[94:95]
	v_pk_add_f32 v[86:87], v[86:87], 1.0 op_sel_hi:[1,0]
	v_cvt_pk_bf16_f32 v92, v82, v83
	v_or_b32_e32 v82, 32, v156
	v_pk_add_f32 v[88:89], v[88:89], 1.0 op_sel_hi:[1,0]
	v_mad_i64_i32 v[82:83], s[44:45], v82, s60, v[114:115]
	v_rcp_f32_e32 v88, v88
	v_rcp_f32_e32 v89, v89
	v_rcp_f32_e32 v86, v86
	v_rcp_f32_e32 v87, v87
	v_pk_mul_f32 v[74:75], v[78:79], v[74:75]
	v_pk_mul_f32 v[78:79], v[72:73], v[84:85] op_sel_hi:[1,0]
	v_pk_mul_f32 v[80:81], v[70:71], v[84:85] op_sel_hi:[1,0]
	v_lshl_add_u64 v[82:83], v[82:83], 0, v[116:117]
	v_exp_f32_e32 v80, v80
	v_exp_f32_e32 v78, v78
	v_exp_f32_e32 v79, v79
	v_exp_f32_e32 v81, v81
; __device__ __forceinline__ f32x4 sig_from_negl2(f32x4 t) { return rcp_4(exp2_4(t) + 1.0f); }
; __device__ __forceinline__ u32x2 pack4(f32x4 v) { u32x2 w; w.x = cvtpk(v[0], v[1]); w.y = cvtpk(v[2], v[3]); return w; }
;     __device__ __forceinline__ void operator()(const Acc& acc, const Unit& u, int wr, int wc, int fr, int fq) const {
;     ...
;             for (int m = 0; m < 4; ++m) {
;                 const int r = u.pm * 256 + ai * 128 + wr * 64 + m * 16 + fr;
;                 const float rs = rsv[ai][m], nrs = -LOG2E * rs, rs2 = rs * rs;
;                 u32x4 w;
; #pragma unroll
;                 for (int n = 0; n < 2; ++n) {
;                     const f32x4 ga = acc[ai][0][m][n], ua = acc[ai][1][m][n];
;                     const f32x4 sg = sig_from_negl2(ga * nrs);
;                     const u32x2 pk = pack4((ga * ua) * rs2 * sg);
;                     if (n == 0) { w.x = pk.x; w.y = pk.y; } else { w.z = pk.x; w.w = pk.y; }
;                 }
;                 *(u32x4*)(O + (size_t)r * DFF + col) = w;
;             }
	global_store_dwordx4 v[82:83], v[90:93], off
	v_mul_f32_e32 v82, v172, v172
	v_pk_mul_f32 v[74:75], v[74:75], v[82:83] op_sel_hi:[1,0]
	v_pk_mul_f32 v[76:77], v[76:77], v[82:83] op_sel_hi:[1,0]
	v_pk_mul_f32 v[74:75], v[74:75], v[88:89]
	v_pk_mul_f32 v[76:77], v[76:77], v[86:87]
	v_cvt_pk_bf16_f32 v74, v74, v75
	v_cvt_pk_bf16_f32 v75, v76, v77
	v_pk_add_f32 v[76:77], v[78:79], 1.0 op_sel_hi:[1,0]
	v_pk_add_f32 v[78:79], v[80:81], 1.0 op_sel_hi:[1,0]
	v_rcp_f32_e32 v76, v76
	v_rcp_f32_e32 v78, v78
	v_rcp_f32_e32 v79, v79
	v_rcp_f32_e32 v77, v77
	v_pk_mul_f32 v[66:67], v[70:71], v[66:67]
	v_pk_mul_f32 v[68:69], v[72:73], v[68:69]
	v_pk_mul_f32 v[66:67], v[66:67], v[82:83] op_sel_hi:[1,0]
	v_pk_mul_f32 v[68:69], v[68:69], v[82:83] op_sel_hi:[1,0]
	v_pk_mul_f32 v[66:67], v[66:67], v[78:79]
	v_pk_mul_f32 v[68:69], v[68:69], v[76:77]
	v_cvt_pk_bf16_f32 v76, v66, v67
	v_or_b32_e32 v66, 48, v156
	v_mad_i64_i32 v[66:67], s[44:45], v66, s60, v[114:115]
	v_cvt_pk_bf16_f32 v77, v68, v69
	v_lshl_add_u64 v[66:67], v[66:67], 0, v[116:117]
	global_store_dwordx4 v[66:67], v[74:77], off
	v_mul_f32_e32 v66, 0xbfb8aa3b, v161
	v_pk_mul_f32 v[68:69], v[64:65], v[66:67] op_sel_hi:[1,0]
	v_pk_mul_f32 v[70:71], v[62:63], v[66:67] op_sel_hi:[1,0]
	v_exp_f32_e32 v68, v68
	v_exp_f32_e32 v70, v70
	v_exp_f32_e32 v69, v69
	v_exp_f32_e32 v71, v71
	v_add_u32_e32 v67, 0x80, v156
	v_pk_mul_f32 v[58:59], v[62:63], v[58:59]
	v_pk_add_f32 v[68:69], v[68:69], 1.0 op_sel_hi:[1,0]
	v_pk_add_f32 v[70:71], v[70:71], 1.0 op_sel_hi:[1,0]
	v_rcp_f32_e32 v68, v68
	v_rcp_f32_e32 v70, v70
	v_rcp_f32_e32 v71, v71
	v_rcp_f32_e32 v69, v69
	v_pk_mul_f32 v[62:63], v[56:57], v[66:67] op_sel_hi:[1,0]
	v_mul_f32_e32 v72, v161, v161
	v_exp_f32_e32 v62, v62
	v_exp_f32_e32 v63, v63
	v_pk_mul_f32 v[60:61], v[64:65], v[60:61]
	v_pk_mul_f32 v[58:59], v[58:59], v[72:73] op_sel_hi:[1,0]
	v_pk_mul_f32 v[60:61], v[60:61], v[72:73] op_sel_hi:[1,0]
	v_pk_mul_f32 v[58:59], v[58:59], v[70:71]
	v_pk_mul_f32 v[60:61], v[60:61], v[68:69]
	v_cvt_pk_bf16_f32 v58, v58, v59
	v_cvt_pk_bf16_f32 v59, v60, v61
	v_pk_add_f32 v[60:61], v[62:63], 1.0 op_sel_hi:[1,0]
	v_pk_mul_f32 v[64:65], v[54:55], v[66:67] op_sel_hi:[1,0]
	v_rcp_f32_e32 v60, v60
	v_rcp_f32_e32 v61, v61
	v_exp_f32_e32 v64, v64
	v_exp_f32_e32 v65, v65
	v_pk_mul_f32 v[52:53], v[56:57], v[52:53]
	v_pk_mul_f32 v[50:51], v[54:55], v[50:51]
	v_pk_mul_f32 v[52:53], v[52:53], v[72:73] op_sel_hi:[1,0]
	v_pk_add_f32 v[62:63], v[64:65], 1.0 op_sel_hi:[1,0]
	v_pk_mul_f32 v[52:53], v[52:53], v[60:61]
	v_rcp_f32_e32 v62, v62
	v_cvt_pk_bf16_f32 v61, v52, v53
	v_mul_f32_e32 v52, 0xbfb8aa3b, v173
	v_pk_mul_f32 v[54:55], v[48:49], v[52:53] op_sel_hi:[1,0]
	v_pk_mul_f32 v[56:57], v[46:47], v[52:53] op_sel_hi:[1,0]
	v_rcp_f32_e32 v63, v63
	v_exp_f32_e32 v56, v56
	v_exp_f32_e32 v54, v54
	v_exp_f32_e32 v55, v55
	v_exp_f32_e32 v57, v57
	v_pk_mul_f32 v[50:51], v[50:51], v[72:73] op_sel_hi:[1,0]
	v_pk_mul_f32 v[42:43], v[46:47], v[42:43]
	v_pk_mul_f32 v[50:51], v[50:51], v[62:63]
	v_pk_add_f32 v[54:55], v[54:55], 1.0 op_sel_hi:[1,0]
	v_pk_add_f32 v[56:57], v[56:57], 1.0 op_sel_hi:[1,0]
	v_cvt_pk_bf16_f32 v60, v50, v51
	v_mad_i64_i32 v[50:51], s[44:45], v67, s60, v[114:115]
	v_rcp_f32_e32 v56, v56
	v_rcp_f32_e32 v57, v57
	v_rcp_f32_e32 v54, v54
	v_rcp_f32_e32 v55, v55
	v_pk_mul_f32 v[46:47], v[40:41], v[52:53] op_sel_hi:[1,0]
	v_lshl_add_u64 v[50:51], v[50:51], 0, v[116:117]
	v_exp_f32_e32 v46, v46
	v_exp_f32_e32 v47, v47
	global_store_dwordx4 v[50:51], v[58:61], off
	v_mul_f32_e32 v50, v173, v173
	v_pk_mul_f32 v[44:45], v[48:49], v[44:45]
	v_pk_mul_f32 v[42:43], v[42:43], v[50:51] op_sel_hi:[1,0]
	v_pk_mul_f32 v[44:45], v[44:45], v[50:51] op_sel_hi:[1,0]
	v_pk_mul_f32 v[42:43], v[42:43], v[56:57]
	v_pk_mul_f32 v[44:45], v[44:45], v[54:55]
	v_cvt_pk_bf16_f32 v42, v42, v43
	v_cvt_pk_bf16_f32 v43, v44, v45
	v_pk_add_f32 v[44:45], v[46:47], 1.0 op_sel_hi:[1,0]
	v_fmamk_f32 v158, v158, 0x3a800000, v155
	v_pk_mul_f32 v[48:49], v[38:39], v[52:53] op_sel_hi:[1,0]
	v_rcp_f32_e32 v44, v44
	v_rcp_f32_e32 v45, v45
	v_rsq_f32_e32 v158, v158
	v_exp_f32_e32 v48, v48
	v_exp_f32_e32 v49, v49
	v_pk_mul_f32 v[36:37], v[40:41], v[36:37]
	v_pk_mul_f32 v[34:35], v[38:39], v[34:35]
	v_pk_mul_f32 v[36:37], v[36:37], v[50:51] op_sel_hi:[1,0]
	v_pk_add_f32 v[46:47], v[48:49], 1.0 op_sel_hi:[1,0]
	v_pk_mul_f32 v[36:37], v[36:37], v[44:45]
	v_rcp_f32_e32 v46, v46
	v_cvt_pk_bf16_f32 v45, v36, v37
	v_mul_f32_e32 v36, 0xbfb8aa3b, v158
	v_rcp_f32_e32 v47, v47
	v_pk_mul_f32 v[38:39], v[32:33], v[36:37] op_sel_hi:[1,0]
; __device__ __forceinline__ f32x4 sig_from_negl2(f32x4 t) { return rcp_4(exp2_4(t) + 1.0f); }
; __device__ __forceinline__ u32x2 pack4(f32x4 v) { u32x2 w; w.x = cvtpk(v[0], v[1]); w.y = cvtpk(v[2], v[3]); return w; }
; #define PG8_BAR __builtin_amdgcn_s_barrier()
; #define PG8_STATS(pm_) do { if constexpr (Epi::STAB) { if (wr == 1) { const char* _sb = (const char*)E.st + (size_t)(pm_) * 16384 + (size_t)lane * 16; \
;         _Pragma("unroll") for (int _i = 0; _i < 4; ++_i) __builtin_amdgcn_global_load_lds((const unsigned*)(_sb + ((wid - 4) + 4 * _i) * 1024), (LAS unsigned*)(lds + STAB_OFF + ((wid - 4) + 4 * _i) * 1024), 16, 0, 0); } } } while (0)
; template <class Epi>
; __device__ __forceinline__ void gemm_phase(LAS unsigned char* lds, const Gemm g, const StaticOrder& S, const Epi& E) {
;     ...
;         if (!has_next) break;
; #pragma unroll
;         for (int a = 0; a < 2; ++a)
; #pragma unroll
;             for (int b = 0; b < 2; ++b)
; #pragma unroll
;                 for (int m = 0; m < 4; ++m)
; #pragma unroll
;                     for (int n = 0; n < 2; ++n) acc[a][b][m][n] = (f32x4){0.f, 0.f, 0.f, 0.f};
;         cur = nxt; cA = nA; cB = nB; ++ui;
;         if (wr == 1) PG8_BAR;
;         PG8_STATS(cur.pm);
;     __device__ __forceinline__ void operator()(const Acc& acc, const Unit& u, int wr, int wc, int fr, int fq) const {
;     ...
;             for (int m = 0; m < 4; ++m) {
;                 const int r = u.pm * 256 + ai * 128 + wr * 64 + m * 16 + fr;
;                 const float rs = rsv[ai][m], nrs = -LOG2E * rs, rs2 = rs * rs;
;                 u32x4 w;
; #pragma unroll
;                 for (int n = 0; n < 2; ++n) {
;                     const f32x4 ga = acc[ai][0][m][n], ua = acc[ai][1][m][n];
;                     const f32x4 sg = sig_from_negl2(ga * nrs);
;                     const u32x2 pk = pack4((ga * ua) * rs2 * sg);
;                     if (n == 0) { w.x = pk.x; w.y = pk.y; } else { w.z = pk.x; w.w = pk.y; }
;                 }
;                 *(u32x4*)(O + (size_t)r * DFF + col) = w;
;             }
	v_pk_mul_f32 v[40:41], v[30:31], v[36:37] op_sel_hi:[1,0]
	v_exp_f32_e32 v38, v38
	v_exp_f32_e32 v40, v40
	v_exp_f32_e32 v39, v39
	v_exp_f32_e32 v41, v41
	v_pk_mul_f32 v[34:35], v[34:35], v[50:51] op_sel_hi:[1,0]
	v_pk_mul_f32 v[26:27], v[30:31], v[26:27]
	v_pk_mul_f32 v[34:35], v[34:35], v[46:47]
	v_pk_add_f32 v[38:39], v[38:39], 1.0 op_sel_hi:[1,0]
	v_cvt_pk_bf16_f32 v44, v34, v35
	v_add_u32_e32 v34, 0x90, v156
	v_pk_add_f32 v[40:41], v[40:41], 1.0 op_sel_hi:[1,0]
	v_mad_i64_i32 v[34:35], s[44:45], v34, s60, v[114:115]
	v_rcp_f32_e32 v40, v40
	v_rcp_f32_e32 v41, v41
	v_rcp_f32_e32 v38, v38
	v_rcp_f32_e32 v39, v39
	v_pk_mul_f32 v[30:31], v[24:25], v[36:37] op_sel_hi:[1,0]
	v_lshl_add_u64 v[34:35], v[34:35], 0, v[116:117]
	v_exp_f32_e32 v30, v30
	v_exp_f32_e32 v31, v31
	global_store_dwordx4 v[34:35], v[42:45], off
	v_mul_f32_e32 v34, v158, v158
	v_pk_mul_f32 v[28:29], v[32:33], v[28:29]
	v_pk_mul_f32 v[26:27], v[26:27], v[34:35] op_sel_hi:[1,0]
	v_pk_mul_f32 v[28:29], v[28:29], v[34:35] op_sel_hi:[1,0]
	v_pk_mul_f32 v[26:27], v[26:27], v[40:41]
	v_pk_mul_f32 v[28:29], v[28:29], v[38:39]
	v_cvt_pk_bf16_f32 v26, v26, v27
	v_cvt_pk_bf16_f32 v27, v28, v29
	v_pk_add_f32 v[28:29], v[30:31], 1.0 op_sel_hi:[1,0]
	v_pk_mul_f32 v[32:33], v[22:23], v[36:37] op_sel_hi:[1,0]
	v_rcp_f32_e32 v28, v28
	v_rcp_f32_e32 v29, v29
	v_exp_f32_e32 v32, v32
	v_exp_f32_e32 v33, v33
	v_pk_mul_f32 v[20:21], v[24:25], v[20:21]
	v_pk_mul_f32 v[18:19], v[22:23], v[18:19]
	v_pk_mul_f32 v[20:21], v[20:21], v[34:35] op_sel_hi:[1,0]
	v_pk_add_f32 v[30:31], v[32:33], 1.0 op_sel_hi:[1,0]
	v_pk_mul_f32 v[20:21], v[20:21], v[28:29]
	v_rcp_f32_e32 v30, v30
	v_cvt_pk_bf16_f32 v29, v20, v21
	v_mul_f32_e32 v20, 0xbfb8aa3b, v157
	v_rcp_f32_e32 v31, v31
	v_pk_mul_f32 v[22:23], v[16:17], v[20:21] op_sel_hi:[1,0]
	v_pk_mul_f32 v[24:25], v[14:15], v[20:21] op_sel_hi:[1,0]
	v_exp_f32_e32 v22, v22
	v_exp_f32_e32 v24, v24
	v_exp_f32_e32 v23, v23
	v_exp_f32_e32 v25, v25
	v_pk_mul_f32 v[18:19], v[18:19], v[34:35] op_sel_hi:[1,0]
	v_pk_mul_f32 v[12:13], v[16:17], v[12:13]
	v_pk_mul_f32 v[18:19], v[18:19], v[30:31]
	v_pk_add_f32 v[22:23], v[22:23], 1.0 op_sel_hi:[1,0]
	v_cvt_pk_bf16_f32 v28, v18, v19
	v_add_u32_e32 v18, 0xa0, v156
	v_pk_add_f32 v[24:25], v[24:25], 1.0 op_sel_hi:[1,0]
	v_mad_i64_i32 v[18:19], s[44:45], v18, s60, v[114:115]
	v_rcp_f32_e32 v24, v24
	v_rcp_f32_e32 v25, v25
	v_rcp_f32_e32 v22, v22
	v_rcp_f32_e32 v23, v23
	v_pk_mul_f32 v[10:11], v[14:15], v[10:11]
	v_pk_mul_f32 v[14:15], v[8:9], v[20:21] op_sel_hi:[1,0]
	v_pk_mul_f32 v[16:17], v[6:7], v[20:21] op_sel_hi:[1,0]
	v_lshl_add_u64 v[18:19], v[18:19], 0, v[116:117]
	v_exp_f32_e32 v16, v16
	v_exp_f32_e32 v14, v14
	v_exp_f32_e32 v15, v15
	v_exp_f32_e32 v17, v17
	global_store_dwordx4 v[18:19], v[26:29], off
	v_mul_f32_e32 v18, v157, v157
	v_pk_mul_f32 v[10:11], v[10:11], v[18:19] op_sel_hi:[1,0]
	v_pk_mul_f32 v[12:13], v[12:13], v[18:19] op_sel_hi:[1,0]
	v_pk_mul_f32 v[10:11], v[10:11], v[24:25]
	v_pk_mul_f32 v[12:13], v[12:13], v[22:23]
	v_cvt_pk_bf16_f32 v10, v10, v11
	v_cvt_pk_bf16_f32 v11, v12, v13
	v_pk_add_f32 v[12:13], v[14:15], 1.0 op_sel_hi:[1,0]
	v_pk_add_f32 v[14:15], v[16:17], 1.0 op_sel_hi:[1,0]
	v_rcp_f32_e32 v12, v12
	v_rcp_f32_e32 v14, v14
	v_rcp_f32_e32 v15, v15
	v_rcp_f32_e32 v13, v13
	v_pk_mul_f32 v[2:3], v[6:7], v[2:3]
	v_pk_mul_f32 v[4:5], v[8:9], v[4:5]
	v_pk_mul_f32 v[2:3], v[2:3], v[18:19] op_sel_hi:[1,0]
	v_pk_mul_f32 v[4:5], v[4:5], v[18:19] op_sel_hi:[1,0]
	v_pk_mul_f32 v[2:3], v[2:3], v[14:15]
	v_pk_mul_f32 v[4:5], v[4:5], v[12:13]
	v_cvt_pk_bf16_f32 v12, v2, v3
	v_add_u32_e32 v2, 0xb0, v156
	v_mad_i64_i32 v[2:3], s[44:45], v2, s60, v[114:115]
	v_cvt_pk_bf16_f32 v13, v4, v5
	v_lshl_add_u64 v[2:3], v[2:3], 0, v[116:117]
	s_andn2_b64 vcc, exec, s[2:3]
	s_mov_b64 s[2:3], -1
	global_store_dwordx4 v[2:3], v[10:13], off
	s_cbranch_vccnz .LBB0_880
	s_and_b64 vcc, exec, s[0:1]
	s_cbranch_vccnz .LBB0_879
	s_lshl_b64 s[2:3], s[24:25], 14
	v_lshl_add_u64 v[2:3], v[138:139], 0, s[2:3]
	s_add_i32 s2, 0, 0x20400
	v_lshl_add_u64 v[4:5], v[2:3], 0, s[12:13]
	s_add_i32 m0, s2, s12
	s_barrier
	global_load_lds_dwordx4 v[4:5], off
	v_lshl_add_u64 v[4:5], v[2:3], 0, s[6:7]
	s_add_i32 m0, s2, s6
	s_nop 0
	global_load_lds_dwordx4 v[4:5], off
	v_lshl_add_u64 v[4:5], v[2:3], 0, s[18:19]
	s_add_i32 m0, s2, s18
	v_lshl_add_u64 v[2:3], v[2:3], 0, s[20:21]
	global_load_lds_dwordx4 v[4:5], off
	s_add_i32 m0, s2, s20
	s_nop 0
	global_load_lds_dwordx4 v[2:3], off
	s_branch .LBB0_879

; __global__ void __launch_bounds__(512, 2) fwd_megakernel(Params P) {
	.amdhsa_kernel _Z14fwd_megakernel6Params
		.amdhsa_group_segment_fixed_size 0
		.amdhsa_private_segment_fixed_size 0
		.amdhsa_kernarg_size 488
		.amdhsa_user_sgpr_count 2
		.amdhsa_user_sgpr_dispatch_ptr 0
		.amdhsa_user_sgpr_queue_ptr 0
		.amdhsa_user_sgpr_kernarg_segment_ptr 1
		.amdhsa_user_sgpr_dispatch_id 0
		.amdhsa_user_sgpr_kernarg_preload_length 0
		.amdhsa_user_sgpr_kernarg_preload_offset 0
		.amdhsa_user_sgpr_private_segment_size 0
		.amdhsa_uses_dynamic_stack 0
		.amdhsa_enable_private_segment 0
		.amdhsa_system_sgpr_workgroup_id_x 1
		.amdhsa_system_sgpr_workgroup_id_y 0
		.amdhsa_system_sgpr_workgroup_id_z 0
		.amdhsa_system_sgpr_workgroup_info 0
		.amdhsa_system_vgpr_workitem_id 2
		.amdhsa_next_free_vgpr 248
		.amdhsa_next_free_sgpr 102
		.amdhsa_accum_offset 248
		.amdhsa_reserve_vcc 1
		.amdhsa_float_round_mode_32 0
		.amdhsa_float_round_mode_16_64 0
		.amdhsa_float_denorm_mode_32 3
		.amdhsa_float_denorm_mode_16_64 3
		.amdhsa_dx10_clamp 1
		.amdhsa_ieee_mode 1
		.amdhsa_fp16_overflow 0
		.amdhsa_tg_split 0
		.amdhsa_exception_fp_ieee_invalid_op 0
		.amdhsa_exception_fp_denorm_src 0
		.amdhsa_exception_fp_ieee_div_zero 0
		.amdhsa_exception_fp_ieee_overflow 0
		.amdhsa_exception_fp_ieee_underflow 0
		.amdhsa_exception_fp_ieee_inexact 0
		.amdhsa_exception_int_div_zero 0
	.end_amdhsa_kernel

; __global__ void __launch_bounds__(512, 2) fwd_megakernel(Params P) {
amdhsa.kernels:
  - .agpr_count:     0
    .args:
      - .offset:         0
        .size:           232
        .value_kind:     by_value
      - .offset:         232
        .size:           4
        .value_kind:     hidden_block_count_x
      - .offset:         236
        .size:           4
        .value_kind:     hidden_block_count_y
      - .offset:         240
        .size:           4
        .value_kind:     hidden_block_count_z
      - .offset:         244
        .size:           2
        .value_kind:     hidden_group_size_x
      - .offset:         246
        .size:           2
        .value_kind:     hidden_group_size_y
      - .offset:         248
        .size:           2
        .value_kind:     hidden_group_size_z
      - .offset:         250
        .size:           2
        .value_kind:     hidden_remainder_x
      - .offset:         252
        .size:           2
        .value_kind:     hidden_remainder_y
      - .offset:         254
        .size:           2
        .value_kind:     hidden_remainder_z
      - .offset:         272
        .size:           8
        .value_kind:     hidden_global_offset_x
      - .offset:         280
        .size:           8
        .value_kind:     hidden_global_offset_y
      - .offset:         288
        .size:           8
        .value_kind:     hidden_global_offset_z
      - .offset:         296
        .size:           2
        .value_kind:     hidden_grid_dims
      - .offset:         320
        .size:           8
        .value_kind:     hidden_multigrid_sync_arg
      - .offset:         352
        .size:           4
        .value_kind:     hidden_dynamic_lds_size
    .group_segment_fixed_size: 0
    .kernarg_segment_align: 8
    .kernarg_segment_size: 488
    .language:       OpenCL C
    .language_version:
      - 2
      - 0
    .max_flat_workgroup_size: 512
    .name:           _Z14fwd_megakernel6Params
    .private_segment_fixed_size: 0
    .sgpr_count:     108
    .sgpr_spill_count: 25
    .symbol:         _Z14fwd_megakernel6Params.kd
    .uniform_work_group_size: 1
    .uses_dynamic_stack: false
    .vgpr_count:     248
    .vgpr_spill_count: 0
    .wavefront_size: 64
